# in-proj q/k/v epilogue: lean straight-line path with SGPR-base + 32-bit-offset stores
# baseline (speedup 1.0000x reference)
; __device__ __forceinline__ unsigned pk2(float lo, float hi) { const f32x2_t f = {lo, hi}; const bf16x2_t b = __builtin_convertvector(f, bf16x2_t); return __builtin_bit_cast(unsigned, b); }
;   __device__ __forceinline__ void operator()(const f32x4 (&acc)[2][2][4][2], const pg8::Unit& u, int wr, int wc, int fr, int fq) const {
;     ...
; #pragma unroll
;         for (int ai = 0; ai < 2; ++ai)
; #pragma unroll
;           for (int m = 0; m < 4; ++m) {
;             const int row = row0 + ai * 128 + m * 16; const float rs = rsv[ai][m];
; #pragma unroll
;             for (int bj = 0; bj < 2; ++bj) {
;               const int c = col0 + bj * 128;
;               f32x4 a = acc[ai][bj][m][0] * rs, b = acc[ai][bj][m][1] * rs;
;               if (isg) {
; #pragma unroll
;                 for (int e = 0; e < 4; ++e) { a[e] = __builtin_amdgcn_rcpf(1.0f + __expf(-a[e])); b[e] = __builtin_amdgcn_rcpf(1.0f + __expf(-b[e])); }
;               }
;               u32x4 o; o.x = pk2(a[0], a[1]); o.y = pk2(a[2], a[3]); o.z = pk2(b[0], b[1]); o.w = pk2(b[2], b[3]);
;               if (isg) *(u32x4*)(sg + (size_t)row * 2048 + (c - 7680)) = o; else *(u32x4*)(qkv + (size_t)row * 4608 + c) = o;
.Lqkv_lean:
	s_movk_i32 s10, 0x2400
	v_lshlrev_b32_e32 v195, 1, v174
	v_mov_b32_e32 v196, s10
	v_mad_u32_u24 v194, v176, v196, v195
	s_mov_b64 s[12:13], s[30:31]
	v_pk_mul_f32 v[150:151], v[126:127], v[148:149] op_sel_hi:[1,0]
	v_pk_mul_f32 v[152:153], v[128:129], v[148:149] op_sel_hi:[1,0]
	v_pk_mul_f32 v[154:155], v[122:123], v[148:149] op_sel_hi:[1,0]
	v_pk_mul_f32 v[156:157], v[124:125], v[148:149] op_sel_hi:[1,0]
	v_cvt_pk_bf16_f32 v158, v150, v151
	v_cvt_pk_bf16_f32 v159, v152, v153
	v_cvt_pk_bf16_f32 v160, v154, v155
	v_cvt_pk_bf16_f32 v161, v156, v157
	global_store_dwordx4 v194, v[158:161], s[12:13]
	v_pk_mul_f32 v[178:179], v[60:61], v[148:149] op_sel_hi:[1,0]
	v_pk_mul_f32 v[180:181], v[62:63], v[148:149] op_sel_hi:[1,0]
	v_pk_mul_f32 v[182:183], v[56:57], v[148:149] op_sel_hi:[1,0]
	v_pk_mul_f32 v[184:185], v[58:59], v[148:149] op_sel_hi:[1,0]
	v_cvt_pk_bf16_f32 v190, v178, v179
	v_cvt_pk_bf16_f32 v191, v180, v181
	v_cvt_pk_bf16_f32 v192, v182, v183
	v_cvt_pk_bf16_f32 v193, v184, v185
	global_store_dwordx4 v194, v[190:193], s[12:13] offset:256
	s_add_u32 s12, s12, 0x24000
	s_addc_u32 s13, s13, 0
	v_pk_mul_f32 v[150:151], v[118:119], v[146:147] op_sel_hi:[1,0]
	v_pk_mul_f32 v[152:153], v[120:121], v[146:147] op_sel_hi:[1,0]
	v_pk_mul_f32 v[154:155], v[114:115], v[146:147] op_sel_hi:[1,0]
	v_pk_mul_f32 v[156:157], v[116:117], v[146:147] op_sel_hi:[1,0]
	v_cvt_pk_bf16_f32 v158, v150, v151
	v_cvt_pk_bf16_f32 v159, v152, v153
	v_cvt_pk_bf16_f32 v160, v154, v155
	v_cvt_pk_bf16_f32 v161, v156, v157
	global_store_dwordx4 v194, v[158:161], s[12:13]
	v_pk_mul_f32 v[178:179], v[52:53], v[146:147] op_sel_hi:[1,0]
	v_pk_mul_f32 v[180:181], v[54:55], v[146:147] op_sel_hi:[1,0]
	v_pk_mul_f32 v[182:183], v[48:49], v[146:147] op_sel_hi:[1,0]
	v_pk_mul_f32 v[184:185], v[50:51], v[146:147] op_sel_hi:[1,0]
	v_cvt_pk_bf16_f32 v190, v178, v179
	v_cvt_pk_bf16_f32 v191, v180, v181
	v_cvt_pk_bf16_f32 v192, v182, v183
	v_cvt_pk_bf16_f32 v193, v184, v185
	global_store_dwordx4 v194, v[190:193], s[12:13] offset:256
	s_add_u32 s12, s12, 0x24000
	s_addc_u32 s13, s13, 0
	v_pk_mul_f32 v[150:151], v[110:111], v[144:145] op_sel_hi:[1,0]
	v_pk_mul_f32 v[152:153], v[112:113], v[144:145] op_sel_hi:[1,0]
	v_pk_mul_f32 v[154:155], v[106:107], v[144:145] op_sel_hi:[1,0]
	v_pk_mul_f32 v[156:157], v[108:109], v[144:145] op_sel_hi:[1,0]
	v_cvt_pk_bf16_f32 v158, v150, v151
	v_cvt_pk_bf16_f32 v159, v152, v153
	v_cvt_pk_bf16_f32 v160, v154, v155
	v_cvt_pk_bf16_f32 v161, v156, v157
	global_store_dwordx4 v194, v[158:161], s[12:13]
	v_pk_mul_f32 v[178:179], v[44:45], v[144:145] op_sel_hi:[1,0]
	v_pk_mul_f32 v[180:181], v[46:47], v[144:145] op_sel_hi:[1,0]
	v_pk_mul_f32 v[182:183], v[40:41], v[144:145] op_sel_hi:[1,0]
	v_pk_mul_f32 v[184:185], v[42:43], v[144:145] op_sel_hi:[1,0]
	v_cvt_pk_bf16_f32 v190, v178, v179
	v_cvt_pk_bf16_f32 v191, v180, v181
	v_cvt_pk_bf16_f32 v192, v182, v183
	v_cvt_pk_bf16_f32 v193, v184, v185
	global_store_dwordx4 v194, v[190:193], s[12:13] offset:256
	s_add_u32 s12, s12, 0x24000
	s_addc_u32 s13, s13, 0
	v_pk_mul_f32 v[150:151], v[102:103], v[142:143] op_sel_hi:[1,0]
	v_pk_mul_f32 v[152:153], v[104:105], v[142:143] op_sel_hi:[1,0]
	v_pk_mul_f32 v[154:155], v[98:99], v[142:143] op_sel_hi:[1,0]
	v_pk_mul_f32 v[156:157], v[100:101], v[142:143] op_sel_hi:[1,0]
	v_cvt_pk_bf16_f32 v158, v150, v151
	v_cvt_pk_bf16_f32 v159, v152, v153
	v_cvt_pk_bf16_f32 v160, v154, v155
	v_cvt_pk_bf16_f32 v161, v156, v157
	global_store_dwordx4 v194, v[158:161], s[12:13]
	v_pk_mul_f32 v[178:179], v[36:37], v[142:143] op_sel_hi:[1,0]
	v_pk_mul_f32 v[180:181], v[38:39], v[142:143] op_sel_hi:[1,0]
	v_pk_mul_f32 v[182:183], v[32:33], v[142:143] op_sel_hi:[1,0]
	v_pk_mul_f32 v[184:185], v[34:35], v[142:143] op_sel_hi:[1,0]
	v_cvt_pk_bf16_f32 v190, v178, v179
	v_cvt_pk_bf16_f32 v191, v180, v181
	v_cvt_pk_bf16_f32 v192, v182, v183
	v_cvt_pk_bf16_f32 v193, v184, v185
; __device__ __forceinline__ unsigned pk2(float lo, float hi) { const f32x2_t f = {lo, hi}; const bf16x2_t b = __builtin_convertvector(f, bf16x2_t); return __builtin_bit_cast(unsigned, b); }
;   __device__ __forceinline__ void operator()(const f32x4 (&acc)[2][2][4][2], const pg8::Unit& u, int wr, int wc, int fr, int fq) const {
;     ...
; #pragma unroll
;         for (int ai = 0; ai < 2; ++ai)
; #pragma unroll
;           for (int m = 0; m < 4; ++m) {
;             const int row = row0 + ai * 128 + m * 16; const float rs = rsv[ai][m];
; #pragma unroll
;             for (int bj = 0; bj < 2; ++bj) {
;               const int c = col0 + bj * 128;
;               f32x4 a = acc[ai][bj][m][0] * rs, b = acc[ai][bj][m][1] * rs;
;               if (isg) {
; #pragma unroll
;                 for (int e = 0; e < 4; ++e) { a[e] = __builtin_amdgcn_rcpf(1.0f + __expf(-a[e])); b[e] = __builtin_amdgcn_rcpf(1.0f + __expf(-b[e])); }
;               }
;               u32x4 o; o.x = pk2(a[0], a[1]); o.y = pk2(a[2], a[3]); o.z = pk2(b[0], b[1]); o.w = pk2(b[2], b[3]);
;               if (isg) *(u32x4*)(sg + (size_t)row * 2048 + (c - 7680)) = o; else *(u32x4*)(qkv + (size_t)row * 4608 + c) = o;
	global_store_dwordx4 v194, v[190:193], s[12:13] offset:256
	s_add_u32 s12, s12, 0xb4000
	s_addc_u32 s13, s13, 0
	v_pk_mul_f32 v[150:151], v[94:95], v[140:141] op_sel_hi:[1,0]
	v_pk_mul_f32 v[152:153], v[96:97], v[140:141] op_sel_hi:[1,0]
	v_pk_mul_f32 v[154:155], v[90:91], v[140:141] op_sel_hi:[1,0]
	v_pk_mul_f32 v[156:157], v[92:93], v[140:141] op_sel_hi:[1,0]
	v_cvt_pk_bf16_f32 v158, v150, v151
	v_cvt_pk_bf16_f32 v159, v152, v153
	v_cvt_pk_bf16_f32 v160, v154, v155
	v_cvt_pk_bf16_f32 v161, v156, v157
	global_store_dwordx4 v194, v[158:161], s[12:13]
	v_pk_mul_f32 v[178:179], v[28:29], v[140:141] op_sel_hi:[1,0]
	v_pk_mul_f32 v[180:181], v[30:31], v[140:141] op_sel_hi:[1,0]
	v_pk_mul_f32 v[182:183], v[24:25], v[140:141] op_sel_hi:[1,0]
	v_pk_mul_f32 v[184:185], v[26:27], v[140:141] op_sel_hi:[1,0]
	v_cvt_pk_bf16_f32 v190, v178, v179
	v_cvt_pk_bf16_f32 v191, v180, v181
	v_cvt_pk_bf16_f32 v192, v182, v183
	v_cvt_pk_bf16_f32 v193, v184, v185
	global_store_dwordx4 v194, v[190:193], s[12:13] offset:256
	s_add_u32 s12, s12, 0x24000
	s_addc_u32 s13, s13, 0
	v_pk_mul_f32 v[150:151], v[86:87], v[138:139] op_sel_hi:[1,0]
	v_pk_mul_f32 v[152:153], v[88:89], v[138:139] op_sel_hi:[1,0]
	v_pk_mul_f32 v[154:155], v[82:83], v[138:139] op_sel_hi:[1,0]
	v_pk_mul_f32 v[156:157], v[84:85], v[138:139] op_sel_hi:[1,0]
	v_cvt_pk_bf16_f32 v158, v150, v151
	v_cvt_pk_bf16_f32 v159, v152, v153
	v_cvt_pk_bf16_f32 v160, v154, v155
	v_cvt_pk_bf16_f32 v161, v156, v157
	global_store_dwordx4 v194, v[158:161], s[12:13]
	v_pk_mul_f32 v[178:179], v[20:21], v[138:139] op_sel_hi:[1,0]
	v_pk_mul_f32 v[180:181], v[22:23], v[138:139] op_sel_hi:[1,0]
	v_pk_mul_f32 v[182:183], v[16:17], v[138:139] op_sel_hi:[1,0]
	v_pk_mul_f32 v[184:185], v[18:19], v[138:139] op_sel_hi:[1,0]
	v_cvt_pk_bf16_f32 v190, v178, v179
	v_cvt_pk_bf16_f32 v191, v180, v181
	v_cvt_pk_bf16_f32 v192, v182, v183
	v_cvt_pk_bf16_f32 v193, v184, v185
	global_store_dwordx4 v194, v[190:193], s[12:13] offset:256
	s_add_u32 s12, s12, 0x24000
	s_addc_u32 s13, s13, 0
	v_pk_mul_f32 v[150:151], v[76:77], v[136:137] op_sel_hi:[1,0]
	v_pk_mul_f32 v[152:153], v[78:79], v[136:137] op_sel_hi:[1,0]
	v_pk_mul_f32 v[154:155], v[72:73], v[136:137] op_sel_hi:[1,0]
	v_pk_mul_f32 v[156:157], v[74:75], v[136:137] op_sel_hi:[1,0]
	v_cvt_pk_bf16_f32 v158, v150, v151
	v_cvt_pk_bf16_f32 v159, v152, v153
	v_cvt_pk_bf16_f32 v160, v154, v155
	v_cvt_pk_bf16_f32 v161, v156, v157
	global_store_dwordx4 v194, v[158:161], s[12:13]
	v_pk_mul_f32 v[178:179], v[12:13], v[136:137] op_sel_hi:[1,0]
	v_pk_mul_f32 v[180:181], v[14:15], v[136:137] op_sel_hi:[1,0]
	v_pk_mul_f32 v[182:183], v[8:9], v[136:137] op_sel_hi:[1,0]
	v_pk_mul_f32 v[184:185], v[10:11], v[136:137] op_sel_hi:[1,0]
	v_cvt_pk_bf16_f32 v190, v178, v179
	v_cvt_pk_bf16_f32 v191, v180, v181
	v_cvt_pk_bf16_f32 v192, v182, v183
	v_cvt_pk_bf16_f32 v193, v184, v185
	global_store_dwordx4 v194, v[190:193], s[12:13] offset:256
	s_add_u32 s12, s12, 0x24000
	s_addc_u32 s13, s13, 0
	v_pk_mul_f32 v[150:151], v[68:69], v[134:135] op_sel_hi:[1,0]
	v_pk_mul_f32 v[152:153], v[70:71], v[134:135] op_sel_hi:[1,0]
	v_pk_mul_f32 v[154:155], v[64:65], v[134:135] op_sel_hi:[1,0]
	v_pk_mul_f32 v[156:157], v[66:67], v[134:135] op_sel_hi:[1,0]
	v_cvt_pk_bf16_f32 v158, v150, v151
	v_cvt_pk_bf16_f32 v159, v152, v153
	v_cvt_pk_bf16_f32 v160, v154, v155
	v_cvt_pk_bf16_f32 v161, v156, v157
	global_store_dwordx4 v194, v[158:161], s[12:13]
	v_pk_mul_f32 v[178:179], v[4:5], v[134:135] op_sel_hi:[1,0]
	v_pk_mul_f32 v[180:181], v[6:7], v[134:135] op_sel_hi:[1,0]
	v_pk_mul_f32 v[182:183], v[0:1], v[134:135] op_sel_hi:[1,0]
	v_pk_mul_f32 v[184:185], v[2:3], v[134:135] op_sel_hi:[1,0]
	v_cvt_pk_bf16_f32 v190, v178, v179
	v_cvt_pk_bf16_f32 v191, v180, v181
	v_cvt_pk_bf16_f32 v192, v182, v183
	v_cvt_pk_bf16_f32 v193, v184, v185
	global_store_dwordx4 v194, v[190:193], s[12:13] offset:256
	s_branch .LBB0_284
